# v5 plus hand-pipelined residual epilogues (out and ffn2 GEMMs): x loads 5 half-groups ahead with counted vmcnt, permlane16 swap for 16-byte bf16 stores
# speedup vs baseline: 1.0402x; 1.0070x over previous
; __device__ __forceinline__ unsigned cvt_pk_bf16(float lo, float hi) { unsigned r; asm volatile("v_cvt_pk_bf16_f32 %0, %1, %2" : "=v"(r) : "v"(lo), "v"(hi)); return r; }
;     __device__ __forceinline__ void operator()(const f32x4 (&acc)[2][2][4][2], const Unit& u, int wr, int wc, int fr, int fq) const {
;     ...
;             for (int m = 0; m < 4; ++m) { const size_t row = rowb + ai * HALF + m * 16; const size_t off = row * 1024 + col0; float s = 0.f;
; #pragma unroll
;                 for (int bj = 0; bj < 2; ++bj) { u32x2 w[2];
; #pragma unroll
;                     for (int n = 0; n < 2; ++n) { const f32x4 xv = *(const __attribute__((address_space(1))) f32x4*)(xin + off + bj * HALF + n * 16);
;                         const f32x4 xn = xv + gv[bj][n] * acc[ai][bj][m][n];
;                         *(__attribute__((address_space(1))) f32x4*)(out + off + bj * HALF + n * 16) = xn;
;                         if (XG) { s += (xn[0] * xn[0] + xn[1] * xn[1]) + (xn[2] * xn[2] + xn[3] * xn[3]); const f32x4 t = xn * Gv[bj][n];
;                             w[n].x = cvt_pk_bf16(t[0], t[1]); w[n].y = cvt_pk_bf16(t[2], t[3]); } }
;                     if (XG) {
;                         const bool odd = (fq & 1) != 0; const u32x2 snd = odd ? w[0] : w[1]; u32x2 rcv; rcv.x = __shfl_xor(snd.x, 16); rcv.y = __shfl_xor(snd.y, 16);
;                         u32x4 o4; if (odd) { o4.x = rcv.x; o4.y = rcv.y; o4.z = w[1].x; o4.w = w[1].y; } else { o4.x = w[0].x; o4.y = w[0].y; o4.z = rcv.x; o4.w = rcv.y; }
;                         *(u32x4*)(XG + off + bj * HALF + (odd ? 12 : 0)) = o4; } }
;                 if (XG) { s += __shfl_xor(s, 16); s += __shfl_xor(s, 32); if (fq == 0) atomicAdd(ssq + row, s); } }
.LBB0_71:
	s_ashr_i32 s45, s44, 31
	s_lshl_b64 s[44:45], s[44:45], 8
	s_add_u32 s35, s44, s64
	s_addc_u32 s39, s45, s68
	v_and_or_b32 v174, v185, 15, s35
	v_mov_b32_e32 v175, s39
	s_and_b64 vcc, exec, s[42:43]
	s_cbranch_vccnz .Lepi_out_orig
	v_lshlrev_b32_e32 v164, 2, v164
	v_lshl_add_u32 v164, v174, 12, v164
	v_bfe_u32 v0, v185, 4, 1
	v_lshrrev_b32_e32 v165, 1, v164
	v_mad_u32_u24 v165, v0, 24, v165
	v_mov_b32_e32 v175, v164
	v_mov_b32_e32 v2, 0
	v_mov_b32_e32 v3, 0
	global_load_dwordx4 v[184:187], v175, s[2:3] offset:0
	global_load_dwordx4 v[188:191], v175, s[2:3] offset:64
	global_load_dwordx4 v[192:195], v175, s[2:3] offset:512
	global_load_dwordx4 v[196:199], v175, s[2:3] offset:576
	v_add_u32_e32 v175, 0x10000, v175
	global_load_dwordx4 v[200:203], v175, s[2:3] offset:0
	global_load_dwordx4 v[204:207], v175, s[2:3] offset:64
	global_load_dwordx4 v[236:239], v175, s[2:3] offset:512
	global_load_dwordx4 v[240:243], v175, s[2:3] offset:576
	v_add_u32_e32 v175, 0x10000, v175
	global_load_dwordx4 v[244:247], v175, s[2:3] offset:0
	global_load_dwordx4 v[248:251], v175, s[2:3] offset:64
	s_waitcnt vmcnt(8)
	v_pk_fma_f32 v[184:185], v[144:145], v[52:53], v[184:185]
	v_pk_fma_f32 v[186:187], v[146:147], v[54:55], v[186:187]
	v_pk_fma_f32 v[188:189], v[140:141], v[56:57], v[188:189]
	v_pk_fma_f32 v[190:191], v[142:143], v[58:59], v[190:191]
	global_store_dwordx4 v164, v[184:187], s[6:7] offset:0
	global_store_dwordx4 v164, v[188:191], s[6:7] offset:64
	global_load_dwordx4 v[144:147], v175, s[2:3] offset:512
	global_load_dwordx4 v[140:143], v175, s[2:3] offset:576
	v_add_u32_e32 v175, 0x10000, v175
	v_pk_fma_f32 v[2:3], v[184:185], v[184:185], v[2:3]
	v_pk_fma_f32 v[2:3], v[186:187], v[186:187], v[2:3]
	v_pk_fma_f32 v[2:3], v[188:189], v[188:189], v[2:3]
	v_pk_fma_f32 v[2:3], v[190:191], v[190:191], v[2:3]
	v_pk_mul_f32 v[252:253], v[184:185], v[170:171]
	v_cvt_pk_bf16_f32 v176, v252, v253
	v_pk_mul_f32 v[252:253], v[186:187], v[172:173]
	v_cvt_pk_bf16_f32 v177, v252, v253
	v_pk_mul_f32 v[252:253], v[188:189], v[166:167]
	v_cvt_pk_bf16_f32 v178, v252, v253
	v_pk_mul_f32 v[252:253], v[190:191], v[168:169]
	v_cvt_pk_bf16_f32 v179, v252, v253
	s_nop 1
	v_permlane16_swap_b32_e32 v176, v178
	v_permlane16_swap_b32_e32 v177, v179
	global_store_dwordx4 v165, v[176:179], s[10:11] offset:0
	s_waitcnt vmcnt(11)
	v_pk_fma_f32 v[192:193], v[136:137], v[48:49], v[192:193]
	v_pk_fma_f32 v[194:195], v[138:139], v[50:51], v[194:195]
	v_pk_fma_f32 v[196:197], v[132:133], v[44:45], v[196:197]
	v_pk_fma_f32 v[198:199], v[134:135], v[46:47], v[198:199]
	global_store_dwordx4 v164, v[192:195], s[6:7] offset:512
	global_store_dwordx4 v164, v[196:199], s[6:7] offset:576
	global_load_dwordx4 v[136:139], v175, s[2:3] offset:0
	global_load_dwordx4 v[132:135], v175, s[2:3] offset:64
	v_pk_fma_f32 v[2:3], v[192:193], v[192:193], v[2:3]
	v_pk_fma_f32 v[2:3], v[194:195], v[194:195], v[2:3]
	v_pk_fma_f32 v[2:3], v[196:197], v[196:197], v[2:3]
	v_pk_fma_f32 v[2:3], v[198:199], v[198:199], v[2:3]
	v_pk_mul_f32 v[252:253], v[192:193], v[160:161]
	v_cvt_pk_bf16_f32 v176, v252, v253
	v_pk_mul_f32 v[252:253], v[194:195], v[162:163]
	v_cvt_pk_bf16_f32 v177, v252, v253
	v_pk_mul_f32 v[252:253], v[196:197], v[156:157]
	v_cvt_pk_bf16_f32 v178, v252, v253
	v_pk_mul_f32 v[252:253], v[198:199], v[158:159]
	v_cvt_pk_bf16_f32 v179, v252, v253
	s_nop 1
	v_permlane16_swap_b32_e32 v176, v178
	v_permlane16_swap_b32_e32 v177, v179
	global_store_dwordx4 v165, v[176:179], s[10:11] offset:256
	v_add_f32_e32 v2, v2, v3
	v_mov_b32_e32 v0, v2
	s_nop 1
	v_permlane16_swap_b32_e32 v2, v0
	v_add_f32_e32 v2, v2, v0
	v_mov_b32_e32 v0, v2
	s_nop 1
	v_permlane32_swap_b32_e32 v2, v0
	v_add_f32_e32 v2, v2, v0
	v_lshrrev_b32_e32 v252, 12, v164
	v_lshlrev_b32_e32 v252, 2, v252
	s_mov_b64 exec, 0xffff
	global_atomic_add_f32 v252, v2, s[14:15]
	s_mov_b64 exec, -1
	v_add_u32_e32 v164, 0x10000, v164
	v_add_u32_e32 v165, 0x8000, v165
	v_mov_b32_e32 v2, 0
	v_mov_b32_e32 v3, 0
	s_waitcnt vmcnt(15)
	v_pk_fma_f32 v[200:201], v[128:129], v[52:53], v[200:201]
	v_pk_fma_f32 v[202:203], v[130:131], v[54:55], v[202:203]
	v_pk_fma_f32 v[204:205], v[124:125], v[56:57], v[204:205]
	v_pk_fma_f32 v[206:207], v[126:127], v[58:59], v[206:207]
	global_store_dwordx4 v164, v[200:203], s[6:7] offset:0
	global_store_dwordx4 v164, v[204:207], s[6:7] offset:64
	global_load_dwordx4 v[128:131], v175, s[2:3] offset:512
	global_load_dwordx4 v[124:127], v175, s[2:3] offset:576
	v_add_u32_e32 v175, 0x50000, v175
	v_pk_fma_f32 v[2:3], v[200:201], v[200:201], v[2:3]
	v_pk_fma_f32 v[2:3], v[202:203], v[202:203], v[2:3]
	v_pk_fma_f32 v[2:3], v[204:205], v[204:205], v[2:3]
	v_pk_fma_f32 v[2:3], v[206:207], v[206:207], v[2:3]
	v_pk_mul_f32 v[252:253], v[200:201], v[170:171]
	v_cvt_pk_bf16_f32 v176, v252, v253
	v_pk_mul_f32 v[252:253], v[202:203], v[172:173]
	v_cvt_pk_bf16_f32 v177, v252, v253
	v_pk_mul_f32 v[252:253], v[204:205], v[166:167]
	v_cvt_pk_bf16_f32 v178, v252, v253
	v_pk_mul_f32 v[252:253], v[206:207], v[168:169]
	v_cvt_pk_bf16_f32 v179, v252, v253
	s_nop 1
	v_permlane16_swap_b32_e32 v176, v178
	v_permlane16_swap_b32_e32 v177, v179
	global_store_dwordx4 v165, v[176:179], s[10:11] offset:0
	s_waitcnt vmcnt(18)
; __device__ __forceinline__ unsigned cvt_pk_bf16(float lo, float hi) { unsigned r; asm volatile("v_cvt_pk_bf16_f32 %0, %1, %2" : "=v"(r) : "v"(lo), "v"(hi)); return r; }
;     __device__ __forceinline__ void operator()(const f32x4 (&acc)[2][2][4][2], const Unit& u, int wr, int wc, int fr, int fq) const {
;     ...
;             for (int m = 0; m < 4; ++m) { const size_t row = rowb + ai * HALF + m * 16; const size_t off = row * 1024 + col0; float s = 0.f;
; #pragma unroll
;                 for (int bj = 0; bj < 2; ++bj) { u32x2 w[2];
; #pragma unroll
;                     for (int n = 0; n < 2; ++n) { const f32x4 xv = *(const __attribute__((address_space(1))) f32x4*)(xin + off + bj * HALF + n * 16);
;                         const f32x4 xn = xv + gv[bj][n] * acc[ai][bj][m][n];
;                         *(__attribute__((address_space(1))) f32x4*)(out + off + bj * HALF + n * 16) = xn;
;                         if (XG) { s += (xn[0] * xn[0] + xn[1] * xn[1]) + (xn[2] * xn[2] + xn[3] * xn[3]); const f32x4 t = xn * Gv[bj][n];
;                             w[n].x = cvt_pk_bf16(t[0], t[1]); w[n].y = cvt_pk_bf16(t[2], t[3]); } }
;                     if (XG) {
;                         const bool odd = (fq & 1) != 0; const u32x2 snd = odd ? w[0] : w[1]; u32x2 rcv; rcv.x = __shfl_xor(snd.x, 16); rcv.y = __shfl_xor(snd.y, 16);
;                         u32x4 o4; if (odd) { o4.x = rcv.x; o4.y = rcv.y; o4.z = w[1].x; o4.w = w[1].y; } else { o4.x = w[0].x; o4.y = w[0].y; o4.z = rcv.x; o4.w = rcv.y; }
;                         *(u32x4*)(XG + off + bj * HALF + (odd ? 12 : 0)) = o4; } }
;                 if (XG) { s += __shfl_xor(s, 16); s += __shfl_xor(s, 32); if (fq == 0) atomicAdd(ssq + row, s); } }
	v_pk_fma_f32 v[236:237], v[120:121], v[48:49], v[236:237]
	v_pk_fma_f32 v[238:239], v[122:123], v[50:51], v[238:239]
	v_pk_fma_f32 v[240:241], v[116:117], v[44:45], v[240:241]
	v_pk_fma_f32 v[242:243], v[118:119], v[46:47], v[242:243]
	global_store_dwordx4 v164, v[236:239], s[6:7] offset:512
	global_store_dwordx4 v164, v[240:243], s[6:7] offset:576
	global_load_dwordx4 v[120:123], v175, s[2:3] offset:0
	global_load_dwordx4 v[116:119], v175, s[2:3] offset:64
	v_pk_fma_f32 v[2:3], v[236:237], v[236:237], v[2:3]
	v_pk_fma_f32 v[2:3], v[238:239], v[238:239], v[2:3]
	v_pk_fma_f32 v[2:3], v[240:241], v[240:241], v[2:3]
	v_pk_fma_f32 v[2:3], v[242:243], v[242:243], v[2:3]
	v_pk_mul_f32 v[252:253], v[236:237], v[160:161]
	v_cvt_pk_bf16_f32 v176, v252, v253
	v_pk_mul_f32 v[252:253], v[238:239], v[162:163]
	v_cvt_pk_bf16_f32 v177, v252, v253
	v_pk_mul_f32 v[252:253], v[240:241], v[156:157]
	v_cvt_pk_bf16_f32 v178, v252, v253
	v_pk_mul_f32 v[252:253], v[242:243], v[158:159]
	v_cvt_pk_bf16_f32 v179, v252, v253
	s_nop 1
	v_permlane16_swap_b32_e32 v176, v178
	v_permlane16_swap_b32_e32 v177, v179
	global_store_dwordx4 v165, v[176:179], s[10:11] offset:256
	v_add_f32_e32 v2, v2, v3
	v_mov_b32_e32 v0, v2
	s_nop 1
	v_permlane16_swap_b32_e32 v2, v0
	v_add_f32_e32 v2, v2, v0
	v_mov_b32_e32 v0, v2
	s_nop 1
	v_permlane32_swap_b32_e32 v2, v0
	v_add_f32_e32 v2, v2, v0
	v_lshrrev_b32_e32 v252, 12, v164
	v_lshlrev_b32_e32 v252, 2, v252
	s_mov_b64 exec, 0xffff
	global_atomic_add_f32 v252, v2, s[14:15]
	s_mov_b64 exec, -1
	v_add_u32_e32 v164, 0x10000, v164
	v_add_u32_e32 v165, 0x8000, v165
	v_mov_b32_e32 v2, 0
	v_mov_b32_e32 v3, 0
	s_waitcnt vmcnt(22)
	v_pk_fma_f32 v[244:245], v[112:113], v[52:53], v[244:245]
	v_pk_fma_f32 v[246:247], v[114:115], v[54:55], v[246:247]
	v_pk_fma_f32 v[248:249], v[108:109], v[56:57], v[248:249]
	v_pk_fma_f32 v[250:251], v[110:111], v[58:59], v[250:251]
	global_store_dwordx4 v164, v[244:247], s[6:7] offset:0
	global_store_dwordx4 v164, v[248:251], s[6:7] offset:64
	global_load_dwordx4 v[112:115], v175, s[2:3] offset:512
	global_load_dwordx4 v[108:111], v175, s[2:3] offset:576
	v_add_u32_e32 v175, 0x10000, v175
	v_pk_fma_f32 v[2:3], v[244:245], v[244:245], v[2:3]
	v_pk_fma_f32 v[2:3], v[246:247], v[246:247], v[2:3]
	v_pk_fma_f32 v[2:3], v[248:249], v[248:249], v[2:3]
	v_pk_fma_f32 v[2:3], v[250:251], v[250:251], v[2:3]
	v_pk_mul_f32 v[252:253], v[244:245], v[170:171]
	v_cvt_pk_bf16_f32 v176, v252, v253
	v_pk_mul_f32 v[252:253], v[246:247], v[172:173]
	v_cvt_pk_bf16_f32 v177, v252, v253
	v_pk_mul_f32 v[252:253], v[248:249], v[166:167]
	v_cvt_pk_bf16_f32 v178, v252, v253
	v_pk_mul_f32 v[252:253], v[250:251], v[168:169]
	v_cvt_pk_bf16_f32 v179, v252, v253
	s_nop 1
	v_permlane16_swap_b32_e32 v176, v178
	v_permlane16_swap_b32_e32 v177, v179
	global_store_dwordx4 v165, v[176:179], s[10:11] offset:0
	s_waitcnt vmcnt(23)
	v_pk_fma_f32 v[144:145], v[104:105], v[48:49], v[144:145]
	v_pk_fma_f32 v[146:147], v[106:107], v[50:51], v[146:147]
	v_pk_fma_f32 v[140:141], v[100:101], v[44:45], v[140:141]
	v_pk_fma_f32 v[142:143], v[102:103], v[46:47], v[142:143]
	global_store_dwordx4 v164, v[144:147], s[6:7] offset:512
	global_store_dwordx4 v164, v[140:143], s[6:7] offset:576
	global_load_dwordx4 v[104:107], v175, s[2:3] offset:0
	global_load_dwordx4 v[100:103], v175, s[2:3] offset:64
	v_pk_fma_f32 v[2:3], v[144:145], v[144:145], v[2:3]
	v_pk_fma_f32 v[2:3], v[146:147], v[146:147], v[2:3]
	v_pk_fma_f32 v[2:3], v[140:141], v[140:141], v[2:3]
	v_pk_fma_f32 v[2:3], v[142:143], v[142:143], v[2:3]
	v_pk_mul_f32 v[252:253], v[144:145], v[160:161]
	v_cvt_pk_bf16_f32 v176, v252, v253
	v_pk_mul_f32 v[252:253], v[146:147], v[162:163]
	v_cvt_pk_bf16_f32 v177, v252, v253
	v_pk_mul_f32 v[252:253], v[140:141], v[156:157]
	v_cvt_pk_bf16_f32 v178, v252, v253
	v_pk_mul_f32 v[252:253], v[142:143], v[158:159]
	v_cvt_pk_bf16_f32 v179, v252, v253
	s_nop 1
	v_permlane16_swap_b32_e32 v176, v178
	v_permlane16_swap_b32_e32 v177, v179
	global_store_dwordx4 v165, v[176:179], s[10:11] offset:256
	v_add_f32_e32 v2, v2, v3
	v_mov_b32_e32 v0, v2
	s_nop 1
	v_permlane16_swap_b32_e32 v2, v0
	v_add_f32_e32 v2, v2, v0
	v_mov_b32_e32 v0, v2
	s_nop 1
	v_permlane32_swap_b32_e32 v2, v0
	v_add_f32_e32 v2, v2, v0
	v_lshrrev_b32_e32 v252, 12, v164
	v_lshlrev_b32_e32 v252, 2, v252
	s_mov_b64 exec, 0xffff
	global_atomic_add_f32 v252, v2, s[14:15]
	s_mov_b64 exec, -1
	v_add_u32_e32 v164, 0x10000, v164
	v_add_u32_e32 v165, 0x8000, v165
	v_mov_b32_e32 v2, 0
	v_mov_b32_e32 v3, 0
	s_waitcnt vmcnt(24)
	v_pk_fma_f32 v[136:137], v[96:97], v[52:53], v[136:137]
	v_pk_fma_f32 v[138:139], v[98:99], v[54:55], v[138:139]
	v_pk_fma_f32 v[132:133], v[92:93], v[56:57], v[132:133]
	v_pk_fma_f32 v[134:135], v[94:95], v[58:59], v[134:135]
	global_store_dwordx4 v164, v[136:139], s[6:7] offset:0
	global_store_dwordx4 v164, v[132:135], s[6:7] offset:64
	global_load_dwordx4 v[96:99], v175, s[2:3] offset:512
	global_load_dwordx4 v[92:95], v175, s[2:3] offset:576
	v_add_u32_e32 v175, 0x10000, v175
	v_pk_fma_f32 v[2:3], v[136:137], v[136:137], v[2:3]
	v_pk_fma_f32 v[2:3], v[138:139], v[138:139], v[2:3]
	v_pk_fma_f32 v[2:3], v[132:133], v[132:133], v[2:3]
	v_pk_fma_f32 v[2:3], v[134:135], v[134:135], v[2:3]
	v_pk_mul_f32 v[252:253], v[136:137], v[170:171]
	v_cvt_pk_bf16_f32 v176, v252, v253
	v_pk_mul_f32 v[252:253], v[138:139], v[172:173]
	v_cvt_pk_bf16_f32 v177, v252, v253
	v_pk_mul_f32 v[252:253], v[132:133], v[166:167]
	v_cvt_pk_bf16_f32 v178, v252, v253
	v_pk_mul_f32 v[252:253], v[134:135], v[168:169]
	v_cvt_pk_bf16_f32 v179, v252, v253
	s_nop 1
	v_permlane16_swap_b32_e32 v176, v178
	v_permlane16_swap_b32_e32 v177, v179
	global_store_dwordx4 v165, v[176:179], s[10:11] offset:0
	s_waitcnt vmcnt(23)
; __device__ __forceinline__ unsigned cvt_pk_bf16(float lo, float hi) { unsigned r; asm volatile("v_cvt_pk_bf16_f32 %0, %1, %2" : "=v"(r) : "v"(lo), "v"(hi)); return r; }
;     __device__ __forceinline__ void operator()(const f32x4 (&acc)[2][2][4][2], const Unit& u, int wr, int wc, int fr, int fq) const {
;     ...
;             for (int m = 0; m < 4; ++m) { const size_t row = rowb + ai * HALF + m * 16; const size_t off = row * 1024 + col0; float s = 0.f;
; #pragma unroll
;                 for (int bj = 0; bj < 2; ++bj) { u32x2 w[2];
; #pragma unroll
;                     for (int n = 0; n < 2; ++n) { const f32x4 xv = *(const __attribute__((address_space(1))) f32x4*)(xin + off + bj * HALF + n * 16);
;                         const f32x4 xn = xv + gv[bj][n] * acc[ai][bj][m][n];
;                         *(__attribute__((address_space(1))) f32x4*)(out + off + bj * HALF + n * 16) = xn;
;                         if (XG) { s += (xn[0] * xn[0] + xn[1] * xn[1]) + (xn[2] * xn[2] + xn[3] * xn[3]); const f32x4 t = xn * Gv[bj][n];
;                             w[n].x = cvt_pk_bf16(t[0], t[1]); w[n].y = cvt_pk_bf16(t[2], t[3]); } }
;                     if (XG) {
;                         const bool odd = (fq & 1) != 0; const u32x2 snd = odd ? w[0] : w[1]; u32x2 rcv; rcv.x = __shfl_xor(snd.x, 16); rcv.y = __shfl_xor(snd.y, 16);
;                         u32x4 o4; if (odd) { o4.x = rcv.x; o4.y = rcv.y; o4.z = w[1].x; o4.w = w[1].y; } else { o4.x = w[0].x; o4.y = w[0].y; o4.z = rcv.x; o4.w = rcv.y; }
;                         *(u32x4*)(XG + off + bj * HALF + (odd ? 12 : 0)) = o4; } }
;                 if (XG) { s += __shfl_xor(s, 16); s += __shfl_xor(s, 32); if (fq == 0) atomicAdd(ssq + row, s); } }
	v_pk_fma_f32 v[128:129], v[88:89], v[48:49], v[128:129]
	v_pk_fma_f32 v[130:131], v[90:91], v[50:51], v[130:131]
	v_pk_fma_f32 v[124:125], v[84:85], v[44:45], v[124:125]
	v_pk_fma_f32 v[126:127], v[86:87], v[46:47], v[126:127]
	global_store_dwordx4 v164, v[128:131], s[6:7] offset:512
	global_store_dwordx4 v164, v[124:127], s[6:7] offset:576
	global_load_dwordx4 v[88:91], v175, s[2:3] offset:0
	global_load_dwordx4 v[84:87], v175, s[2:3] offset:64
	v_pk_fma_f32 v[2:3], v[128:129], v[128:129], v[2:3]
	v_pk_fma_f32 v[2:3], v[130:131], v[130:131], v[2:3]
	v_pk_fma_f32 v[2:3], v[124:125], v[124:125], v[2:3]
	v_pk_fma_f32 v[2:3], v[126:127], v[126:127], v[2:3]
	v_pk_mul_f32 v[252:253], v[128:129], v[160:161]
	v_cvt_pk_bf16_f32 v176, v252, v253
	v_pk_mul_f32 v[252:253], v[130:131], v[162:163]
	v_cvt_pk_bf16_f32 v177, v252, v253
	v_pk_mul_f32 v[252:253], v[124:125], v[156:157]
	v_cvt_pk_bf16_f32 v178, v252, v253
	v_pk_mul_f32 v[252:253], v[126:127], v[158:159]
	v_cvt_pk_bf16_f32 v179, v252, v253
	s_nop 1
	v_permlane16_swap_b32_e32 v176, v178
	v_permlane16_swap_b32_e32 v177, v179
	global_store_dwordx4 v165, v[176:179], s[10:11] offset:256
	v_add_f32_e32 v2, v2, v3
	v_mov_b32_e32 v0, v2
	s_nop 1
	v_permlane16_swap_b32_e32 v2, v0
	v_add_f32_e32 v2, v2, v0
	v_mov_b32_e32 v0, v2
	s_nop 1
	v_permlane32_swap_b32_e32 v2, v0
	v_add_f32_e32 v2, v2, v0
	v_lshrrev_b32_e32 v252, 12, v164
	v_lshlrev_b32_e32 v252, 2, v252
	s_mov_b64 exec, 0xffff
	global_atomic_add_f32 v252, v2, s[14:15]
	s_mov_b64 exec, -1
	v_add_u32_e32 v164, 0x50000, v164
	v_add_u32_e32 v165, 0x28000, v165
	v_mov_b32_e32 v2, 0
	v_mov_b32_e32 v3, 0
	s_waitcnt vmcnt(24)
	v_pk_fma_f32 v[120:121], v[80:81], v[52:53], v[120:121]
	v_pk_fma_f32 v[122:123], v[82:83], v[54:55], v[122:123]
	v_pk_fma_f32 v[116:117], v[76:77], v[56:57], v[116:117]
	v_pk_fma_f32 v[118:119], v[78:79], v[58:59], v[118:119]
	global_store_dwordx4 v164, v[120:123], s[6:7] offset:0
	global_store_dwordx4 v164, v[116:119], s[6:7] offset:64
	global_load_dwordx4 v[80:83], v175, s[2:3] offset:512
	global_load_dwordx4 v[76:79], v175, s[2:3] offset:576
	v_add_u32_e32 v175, 0x10000, v175
	v_pk_fma_f32 v[2:3], v[120:121], v[120:121], v[2:3]
	v_pk_fma_f32 v[2:3], v[122:123], v[122:123], v[2:3]
	v_pk_fma_f32 v[2:3], v[116:117], v[116:117], v[2:3]
	v_pk_fma_f32 v[2:3], v[118:119], v[118:119], v[2:3]
	v_pk_mul_f32 v[252:253], v[120:121], v[170:171]
	v_cvt_pk_bf16_f32 v176, v252, v253
	v_pk_mul_f32 v[252:253], v[122:123], v[172:173]
	v_cvt_pk_bf16_f32 v177, v252, v253
	v_pk_mul_f32 v[252:253], v[116:117], v[166:167]
	v_cvt_pk_bf16_f32 v178, v252, v253
	v_pk_mul_f32 v[252:253], v[118:119], v[168:169]
	v_cvt_pk_bf16_f32 v179, v252, v253
	s_nop 1
	v_permlane16_swap_b32_e32 v176, v178
	v_permlane16_swap_b32_e32 v177, v179
	global_store_dwordx4 v165, v[176:179], s[10:11] offset:0
	s_waitcnt vmcnt(23)
	v_pk_fma_f32 v[112:113], v[72:73], v[48:49], v[112:113]
	v_pk_fma_f32 v[114:115], v[74:75], v[50:51], v[114:115]
	v_pk_fma_f32 v[108:109], v[68:69], v[44:45], v[108:109]
	v_pk_fma_f32 v[110:111], v[70:71], v[46:47], v[110:111]
	global_store_dwordx4 v164, v[112:115], s[6:7] offset:512
	global_store_dwordx4 v164, v[108:111], s[6:7] offset:576
	global_load_dwordx4 v[72:75], v175, s[2:3] offset:0
	global_load_dwordx4 v[68:71], v175, s[2:3] offset:64
	v_pk_fma_f32 v[2:3], v[112:113], v[112:113], v[2:3]
	v_pk_fma_f32 v[2:3], v[114:115], v[114:115], v[2:3]
	v_pk_fma_f32 v[2:3], v[108:109], v[108:109], v[2:3]
	v_pk_fma_f32 v[2:3], v[110:111], v[110:111], v[2:3]
	v_pk_mul_f32 v[252:253], v[112:113], v[160:161]
	v_cvt_pk_bf16_f32 v176, v252, v253
	v_pk_mul_f32 v[252:253], v[114:115], v[162:163]
	v_cvt_pk_bf16_f32 v177, v252, v253
	v_pk_mul_f32 v[252:253], v[108:109], v[156:157]
	v_cvt_pk_bf16_f32 v178, v252, v253
	v_pk_mul_f32 v[252:253], v[110:111], v[158:159]
	v_cvt_pk_bf16_f32 v179, v252, v253
	s_nop 1
	v_permlane16_swap_b32_e32 v176, v178
	v_permlane16_swap_b32_e32 v177, v179
	global_store_dwordx4 v165, v[176:179], s[10:11] offset:256
	v_add_f32_e32 v2, v2, v3
	v_mov_b32_e32 v0, v2
	s_nop 1
	v_permlane16_swap_b32_e32 v2, v0
	v_add_f32_e32 v2, v2, v0
	v_mov_b32_e32 v0, v2
	s_nop 1
	v_permlane32_swap_b32_e32 v2, v0
	v_add_f32_e32 v2, v2, v0
	v_lshrrev_b32_e32 v252, 12, v164
	v_lshlrev_b32_e32 v252, 2, v252
	s_mov_b64 exec, 0xffff
	global_atomic_add_f32 v252, v2, s[14:15]
	s_mov_b64 exec, -1
	v_add_u32_e32 v164, 0x10000, v164
	v_add_u32_e32 v165, 0x8000, v165
	v_mov_b32_e32 v2, 0
	v_mov_b32_e32 v3, 0
	s_waitcnt vmcnt(24)
	v_pk_fma_f32 v[104:105], v[64:65], v[52:53], v[104:105]
	v_pk_fma_f32 v[106:107], v[66:67], v[54:55], v[106:107]
	v_pk_fma_f32 v[100:101], v[60:61], v[56:57], v[100:101]
	v_pk_fma_f32 v[102:103], v[62:63], v[58:59], v[102:103]
	global_store_dwordx4 v164, v[104:107], s[6:7] offset:0
	global_store_dwordx4 v164, v[100:103], s[6:7] offset:64
	global_load_dwordx4 v[64:67], v175, s[2:3] offset:512
	global_load_dwordx4 v[60:63], v175, s[2:3] offset:576
	v_pk_fma_f32 v[2:3], v[104:105], v[104:105], v[2:3]
	v_pk_fma_f32 v[2:3], v[106:107], v[106:107], v[2:3]
	v_pk_fma_f32 v[2:3], v[100:101], v[100:101], v[2:3]
	v_pk_fma_f32 v[2:3], v[102:103], v[102:103], v[2:3]
	v_pk_mul_f32 v[252:253], v[104:105], v[170:171]
	v_cvt_pk_bf16_f32 v176, v252, v253
	v_pk_mul_f32 v[252:253], v[106:107], v[172:173]
	v_cvt_pk_bf16_f32 v177, v252, v253
	v_pk_mul_f32 v[252:253], v[100:101], v[166:167]
	v_cvt_pk_bf16_f32 v178, v252, v253
	v_pk_mul_f32 v[252:253], v[102:103], v[168:169]
	v_cvt_pk_bf16_f32 v179, v252, v253
	s_nop 1
	v_permlane16_swap_b32_e32 v176, v178
	v_permlane16_swap_b32_e32 v177, v179
	global_store_dwordx4 v165, v[176:179], s[10:11] offset:0
	s_waitcnt vmcnt(23)
; __device__ __forceinline__ unsigned cvt_pk_bf16(float lo, float hi) { unsigned r; asm volatile("v_cvt_pk_bf16_f32 %0, %1, %2" : "=v"(r) : "v"(lo), "v"(hi)); return r; }
;     __device__ __forceinline__ void operator()(const f32x4 (&acc)[2][2][4][2], const Unit& u, int wr, int wc, int fr, int fq) const {
;     ...
;             for (int m = 0; m < 4; ++m) { const size_t row = rowb + ai * HALF + m * 16; const size_t off = row * 1024 + col0; float s = 0.f;
; #pragma unroll
;                 for (int bj = 0; bj < 2; ++bj) { u32x2 w[2];
; #pragma unroll
;                     for (int n = 0; n < 2; ++n) { const f32x4 xv = *(const __attribute__((address_space(1))) f32x4*)(xin + off + bj * HALF + n * 16);
;                         const f32x4 xn = xv + gv[bj][n] * acc[ai][bj][m][n];
;                         *(__attribute__((address_space(1))) f32x4*)(out + off + bj * HALF + n * 16) = xn;
;                         if (XG) { s += (xn[0] * xn[0] + xn[1] * xn[1]) + (xn[2] * xn[2] + xn[3] * xn[3]); const f32x4 t = xn * Gv[bj][n];
;                             w[n].x = cvt_pk_bf16(t[0], t[1]); w[n].y = cvt_pk_bf16(t[2], t[3]); } }
;                     if (XG) {
;                         const bool odd = (fq & 1) != 0; const u32x2 snd = odd ? w[0] : w[1]; u32x2 rcv; rcv.x = __shfl_xor(snd.x, 16); rcv.y = __shfl_xor(snd.y, 16);
;                         u32x4 o4; if (odd) { o4.x = rcv.x; o4.y = rcv.y; o4.z = w[1].x; o4.w = w[1].y; } else { o4.x = w[0].x; o4.y = w[0].y; o4.z = rcv.x; o4.w = rcv.y; }
;                         *(u32x4*)(XG + off + bj * HALF + (odd ? 12 : 0)) = o4; } }
;                 if (XG) { s += __shfl_xor(s, 16); s += __shfl_xor(s, 32); if (fq == 0) atomicAdd(ssq + row, s); } }
	v_pk_fma_f32 v[96:97], v[40:41], v[48:49], v[96:97]
	v_pk_fma_f32 v[98:99], v[42:43], v[50:51], v[98:99]
	v_pk_fma_f32 v[92:93], v[36:37], v[44:45], v[92:93]
	v_pk_fma_f32 v[94:95], v[38:39], v[46:47], v[94:95]
	global_store_dwordx4 v164, v[96:99], s[6:7] offset:512
	global_store_dwordx4 v164, v[92:95], s[6:7] offset:576
	v_pk_fma_f32 v[2:3], v[96:97], v[96:97], v[2:3]
	v_pk_fma_f32 v[2:3], v[98:99], v[98:99], v[2:3]
	v_pk_fma_f32 v[2:3], v[92:93], v[92:93], v[2:3]
	v_pk_fma_f32 v[2:3], v[94:95], v[94:95], v[2:3]
	v_pk_mul_f32 v[252:253], v[96:97], v[160:161]
	v_cvt_pk_bf16_f32 v176, v252, v253
	v_pk_mul_f32 v[252:253], v[98:99], v[162:163]
	v_cvt_pk_bf16_f32 v177, v252, v253
	v_pk_mul_f32 v[252:253], v[92:93], v[156:157]
	v_cvt_pk_bf16_f32 v178, v252, v253
	v_pk_mul_f32 v[252:253], v[94:95], v[158:159]
	v_cvt_pk_bf16_f32 v179, v252, v253
	s_nop 1
	v_permlane16_swap_b32_e32 v176, v178
	v_permlane16_swap_b32_e32 v177, v179
	global_store_dwordx4 v165, v[176:179], s[10:11] offset:256
	v_add_f32_e32 v2, v2, v3
	v_mov_b32_e32 v0, v2
	s_nop 1
	v_permlane16_swap_b32_e32 v2, v0
	v_add_f32_e32 v2, v2, v0
	v_mov_b32_e32 v0, v2
	s_nop 1
	v_permlane32_swap_b32_e32 v2, v0
	v_add_f32_e32 v2, v2, v0
	v_lshrrev_b32_e32 v252, 12, v164
	v_lshlrev_b32_e32 v252, 2, v252
	s_mov_b64 exec, 0xffff
	global_atomic_add_f32 v252, v2, s[14:15]
	s_mov_b64 exec, -1
	v_add_u32_e32 v164, 0x10000, v164
	v_add_u32_e32 v165, 0x8000, v165
	v_mov_b32_e32 v2, 0
	v_mov_b32_e32 v3, 0
	s_waitcnt vmcnt(22)
	v_pk_fma_f32 v[88:89], v[32:33], v[52:53], v[88:89]
	v_pk_fma_f32 v[90:91], v[34:35], v[54:55], v[90:91]
	v_pk_fma_f32 v[84:85], v[28:29], v[56:57], v[84:85]
	v_pk_fma_f32 v[86:87], v[30:31], v[58:59], v[86:87]
	global_store_dwordx4 v164, v[88:91], s[6:7] offset:0
	global_store_dwordx4 v164, v[84:87], s[6:7] offset:64
	v_pk_fma_f32 v[2:3], v[88:89], v[88:89], v[2:3]
	v_pk_fma_f32 v[2:3], v[90:91], v[90:91], v[2:3]
	v_pk_fma_f32 v[2:3], v[84:85], v[84:85], v[2:3]
	v_pk_fma_f32 v[2:3], v[86:87], v[86:87], v[2:3]
	v_pk_mul_f32 v[252:253], v[88:89], v[170:171]
	v_cvt_pk_bf16_f32 v176, v252, v253
	v_pk_mul_f32 v[252:253], v[90:91], v[172:173]
	v_cvt_pk_bf16_f32 v177, v252, v253
	v_pk_mul_f32 v[252:253], v[84:85], v[166:167]
	v_cvt_pk_bf16_f32 v178, v252, v253
	v_pk_mul_f32 v[252:253], v[86:87], v[168:169]
	v_cvt_pk_bf16_f32 v179, v252, v253
	s_nop 1
	v_permlane16_swap_b32_e32 v176, v178
	v_permlane16_swap_b32_e32 v177, v179
	global_store_dwordx4 v165, v[176:179], s[10:11] offset:0
	s_waitcnt vmcnt(19)
	v_pk_fma_f32 v[80:81], v[24:25], v[48:49], v[80:81]
	v_pk_fma_f32 v[82:83], v[26:27], v[50:51], v[82:83]
	v_pk_fma_f32 v[76:77], v[20:21], v[44:45], v[76:77]
	v_pk_fma_f32 v[78:79], v[22:23], v[46:47], v[78:79]
	global_store_dwordx4 v164, v[80:83], s[6:7] offset:512
	global_store_dwordx4 v164, v[76:79], s[6:7] offset:576
	v_pk_fma_f32 v[2:3], v[80:81], v[80:81], v[2:3]
	v_pk_fma_f32 v[2:3], v[82:83], v[82:83], v[2:3]
	v_pk_fma_f32 v[2:3], v[76:77], v[76:77], v[2:3]
	v_pk_fma_f32 v[2:3], v[78:79], v[78:79], v[2:3]
	v_pk_mul_f32 v[252:253], v[80:81], v[160:161]
	v_cvt_pk_bf16_f32 v176, v252, v253
	v_pk_mul_f32 v[252:253], v[82:83], v[162:163]
	v_cvt_pk_bf16_f32 v177, v252, v253
	v_pk_mul_f32 v[252:253], v[76:77], v[156:157]
	v_cvt_pk_bf16_f32 v178, v252, v253
	v_pk_mul_f32 v[252:253], v[78:79], v[158:159]
	v_cvt_pk_bf16_f32 v179, v252, v253
	s_nop 1
	v_permlane16_swap_b32_e32 v176, v178
	v_permlane16_swap_b32_e32 v177, v179
	global_store_dwordx4 v165, v[176:179], s[10:11] offset:256
	v_add_f32_e32 v2, v2, v3
	v_mov_b32_e32 v0, v2
	s_nop 1
	v_permlane16_swap_b32_e32 v2, v0
	v_add_f32_e32 v2, v2, v0
	v_mov_b32_e32 v0, v2
	s_nop 1
	v_permlane32_swap_b32_e32 v2, v0
	v_add_f32_e32 v2, v2, v0
	v_lshrrev_b32_e32 v252, 12, v164
	v_lshlrev_b32_e32 v252, 2, v252
	s_mov_b64 exec, 0xffff
	global_atomic_add_f32 v252, v2, s[14:15]
	s_mov_b64 exec, -1
	v_add_u32_e32 v164, 0x10000, v164
	v_add_u32_e32 v165, 0x8000, v165
	v_mov_b32_e32 v2, 0
	v_mov_b32_e32 v3, 0
	s_waitcnt vmcnt(18)
	v_pk_fma_f32 v[72:73], v[16:17], v[52:53], v[72:73]
	v_pk_fma_f32 v[74:75], v[18:19], v[54:55], v[74:75]
	v_pk_fma_f32 v[68:69], v[12:13], v[56:57], v[68:69]
	v_pk_fma_f32 v[70:71], v[14:15], v[58:59], v[70:71]
	global_store_dwordx4 v164, v[72:75], s[6:7] offset:0
	global_store_dwordx4 v164, v[68:71], s[6:7] offset:64
	v_pk_fma_f32 v[2:3], v[72:73], v[72:73], v[2:3]
	v_pk_fma_f32 v[2:3], v[74:75], v[74:75], v[2:3]
	v_pk_fma_f32 v[2:3], v[68:69], v[68:69], v[2:3]
	v_pk_fma_f32 v[2:3], v[70:71], v[70:71], v[2:3]
	v_pk_mul_f32 v[252:253], v[72:73], v[170:171]
	v_cvt_pk_bf16_f32 v176, v252, v253
	v_pk_mul_f32 v[252:253], v[74:75], v[172:173]
	v_cvt_pk_bf16_f32 v177, v252, v253
	v_pk_mul_f32 v[252:253], v[68:69], v[166:167]
	v_cvt_pk_bf16_f32 v178, v252, v253
	v_pk_mul_f32 v[252:253], v[70:71], v[168:169]
	v_cvt_pk_bf16_f32 v179, v252, v253
	s_nop 1
	v_permlane16_swap_b32_e32 v176, v178
	v_permlane16_swap_b32_e32 v177, v179
	global_store_dwordx4 v165, v[176:179], s[10:11] offset:0
	s_waitcnt vmcnt(15)
	v_pk_fma_f32 v[64:65], v[8:9], v[48:49], v[64:65]
	v_pk_fma_f32 v[66:67], v[10:11], v[50:51], v[66:67]
	v_pk_fma_f32 v[60:61], v[4:5], v[44:45], v[60:61]
	v_pk_fma_f32 v[62:63], v[6:7], v[46:47], v[62:63]
	global_store_dwordx4 v164, v[64:67], s[6:7] offset:512
	global_store_dwordx4 v164, v[60:63], s[6:7] offset:576
	v_pk_fma_f32 v[2:3], v[64:65], v[64:65], v[2:3]
	v_pk_fma_f32 v[2:3], v[66:67], v[66:67], v[2:3]
	v_pk_fma_f32 v[2:3], v[60:61], v[60:61], v[2:3]
	v_pk_fma_f32 v[2:3], v[62:63], v[62:63], v[2:3]
	v_pk_mul_f32 v[252:253], v[64:65], v[160:161]
	v_cvt_pk_bf16_f32 v176, v252, v253
	v_pk_mul_f32 v[252:253], v[66:67], v[162:163]
	v_cvt_pk_bf16_f32 v177, v252, v253
	v_pk_mul_f32 v[252:253], v[60:61], v[156:157]
	v_cvt_pk_bf16_f32 v178, v252, v253
	v_pk_mul_f32 v[252:253], v[62:63], v[158:159]
	v_cvt_pk_bf16_f32 v179, v252, v253
	s_nop 1
	v_permlane16_swap_b32_e32 v176, v178
	v_permlane16_swap_b32_e32 v177, v179
	global_store_dwordx4 v165, v[176:179], s[10:11] offset:256
	v_add_f32_e32 v2, v2, v3
	v_mov_b32_e32 v0, v2
	s_nop 1
	v_permlane16_swap_b32_e32 v2, v0
	v_add_f32_e32 v2, v2, v0
	v_mov_b32_e32 v0, v2
	s_nop 1
	v_permlane32_swap_b32_e32 v2, v0
	v_add_f32_e32 v2, v2, v0
	v_lshrrev_b32_e32 v252, 12, v164
	v_lshlrev_b32_e32 v252, 2, v252
	s_mov_b64 exec, 0xffff
	global_atomic_add_f32 v252, v2, s[14:15]
	s_mov_b64 exec, -1
	s_branch .LBB0_188
; __device__ __forceinline__ unsigned cvt_pk_bf16(float lo, float hi) { unsigned r; asm volatile("v_cvt_pk_bf16_f32 %0, %1, %2" : "=v"(r) : "v"(lo), "v"(hi)); return r; }
;     __device__ __forceinline__ void operator()(const f32x4 (&acc)[2][2][4][2], const Unit& u, int wr, int wc, int fr, int fq) const {
;     ...
;                     for (int n = 0; n < 2; ++n) { const f32x4 xv = *(const __attribute__((address_space(1))) f32x4*)(xin + off + bj * HALF + n * 16);
;                         const f32x4 xn = xv + gv[bj][n] * acc[ai][bj][m][n];
;                         *(__attribute__((address_space(1))) f32x4*)(out + off + bj * HALF + n * 16) = xn;
;                         if (XG) { s += (xn[0] * xn[0] + xn[1] * xn[1]) + (xn[2] * xn[2] + xn[3] * xn[3]); const f32x4 t = xn * Gv[bj][n];
;                             w[n].x = cvt_pk_bf16(t[0], t[1]); w[n].y = cvt_pk_bf16(t[2], t[3]); } }
.Lepi_out_orig:
	v_lshlrev_b64 v[2:3], 10, v[174:175]
	v_lshl_add_u64 v[180:181], v[2:3], 0, v[164:165]
	v_lshlrev_b64 v[2:3], 2, v[180:181]
	v_lshl_add_u64 v[178:179], s[2:3], 0, v[2:3]
	global_load_dwordx4 v[186:189], v[178:179], off
	v_lshl_add_u64 v[176:177], s[6:7], 0, v[2:3]
	s_and_b64 vcc, exec, s[42:43]
	s_waitcnt vmcnt(0)
	v_pk_fma_f32 v[146:147], v[146:147], v[54:55], v[188:189]
	v_pk_fma_f32 v[144:145], v[144:145], v[52:53], v[186:187]
	global_store_dwordx4 v[176:177], v[144:147], off
	s_cbranch_vccnz .LBB0_73
	v_pk_mul_f32 v[2:3], v[146:147], v[146:147]
	v_pk_mul_f32 v[186:187], v[144:145], v[144:145]
	v_pk_mul_f32 v[144:145], v[170:171], v[144:145]
	v_pk_mov_b32 v[188:189], v[186:187], v[2:3] op_sel:[1,0]
	v_mov_b32_e32 v187, v3
	v_pk_add_f32 v[2:3], v[188:189], v[186:187]
	v_cvt_pk_bf16_f32 v144, v144, v145
	s_nop 0
	v_add_f32_e32 v186, v2, v3
	v_pk_mul_f32 v[2:3], v[172:173], v[146:147]
	v_mov_b32_e32 v146, v1
	v_mov_b32_e32 v147, v1
	v_cvt_pk_bf16_f32 v145, v2, v3
	s_branch .LBB0_74

; __device__ __forceinline__ unsigned cvt_pk_bf16(float lo, float hi) { unsigned r; asm volatile("v_cvt_pk_bf16_f32 %0, %1, %2" : "=v"(r) : "v"(lo), "v"(hi)); return r; }
;     __device__ __forceinline__ void operator()(const f32x4 (&acc)[2][2][4][2], const Unit& u, int wr, int wc, int fr, int fq) const {
;     ...
;             for (int m = 0; m < 4; ++m) { const size_t row = rowb + ai * HALF + m * 16; const size_t off = row * 1024 + col0; float s = 0.f;
; #pragma unroll
;                 for (int bj = 0; bj < 2; ++bj) { u32x2 w[2];
; #pragma unroll
;                     for (int n = 0; n < 2; ++n) { const f32x4 xv = *(const __attribute__((address_space(1))) f32x4*)(xin + off + bj * HALF + n * 16);
;                         const f32x4 xn = xv + gv[bj][n] * acc[ai][bj][m][n];
;                         *(__attribute__((address_space(1))) f32x4*)(out + off + bj * HALF + n * 16) = xn;
;                         if (XG) { s += (xn[0] * xn[0] + xn[1] * xn[1]) + (xn[2] * xn[2] + xn[3] * xn[3]); const f32x4 t = xn * Gv[bj][n];
;                             w[n].x = cvt_pk_bf16(t[0], t[1]); w[n].y = cvt_pk_bf16(t[2], t[3]); } }
;                     if (XG) {
;                         const bool odd = (fq & 1) != 0; const u32x2 snd = odd ? w[0] : w[1]; u32x2 rcv; rcv.x = __shfl_xor(snd.x, 16); rcv.y = __shfl_xor(snd.y, 16);
;                         u32x4 o4; if (odd) { o4.x = rcv.x; o4.y = rcv.y; o4.z = w[1].x; o4.w = w[1].y; } else { o4.x = w[0].x; o4.y = w[0].y; o4.z = rcv.x; o4.w = rcv.y; }
;                         *(u32x4*)(XG + off + bj * HALF + (odd ? 12 : 0)) = o4; } }
;                 if (XG) { s += __shfl_xor(s, 16); s += __shfl_xor(s, 32); if (fq == 0) atomicAdd(ssq + row, s); } }
.LBB0_702:
	s_ashr_i32 s19, s18, 31
	s_lshl_b64 s[18:19], s[18:19], 8
	s_add_u32 s18, s18, s61
	s_addc_u32 s19, s19, s65
	v_and_or_b32 v174, v183, 15, s18
	v_mov_b32_e32 v175, s19
	s_and_b64 vcc, exec, s[42:43]
	s_cbranch_vccnz .Lepi_ffn2_orig
	v_lshlrev_b32_e32 v164, 2, v164
	v_lshl_add_u32 v164, v174, 12, v164
	v_bfe_u32 v0, v183, 4, 1
	v_lshrrev_b32_e32 v165, 1, v164
	v_mad_u32_u24 v165, v0, 24, v165
	v_mov_b32_e32 v175, v164
	v_mov_b32_e32 v2, 0
	v_mov_b32_e32 v3, 0
	global_load_dwordx4 v[182:185], v175, s[2:3] offset:0
	global_load_dwordx4 v[186:189], v175, s[2:3] offset:64
	global_load_dwordx4 v[190:193], v175, s[2:3] offset:512
	global_load_dwordx4 v[194:197], v175, s[2:3] offset:576
	v_add_u32_e32 v175, 0x10000, v175
	global_load_dwordx4 v[198:201], v175, s[2:3] offset:0
	global_load_dwordx4 v[202:205], v175, s[2:3] offset:64
	global_load_dwordx4 v[236:239], v175, s[2:3] offset:512
	global_load_dwordx4 v[240:243], v175, s[2:3] offset:576
	v_add_u32_e32 v175, 0x10000, v175
	global_load_dwordx4 v[244:247], v175, s[2:3] offset:0
	global_load_dwordx4 v[248:251], v175, s[2:3] offset:64
	s_waitcnt vmcnt(8)
	v_pk_fma_f32 v[182:183], v[64:65], v[72:73], v[182:183]
	v_pk_fma_f32 v[184:185], v[66:67], v[74:75], v[184:185]
	v_pk_fma_f32 v[186:187], v[144:145], v[76:77], v[186:187]
	v_pk_fma_f32 v[188:189], v[146:147], v[78:79], v[188:189]
	global_store_dwordx4 v164, v[182:185], s[2:3] offset:0
	global_store_dwordx4 v164, v[186:189], s[2:3] offset:64
	global_load_dwordx4 v[64:67], v175, s[2:3] offset:512
	global_load_dwordx4 v[144:147], v175, s[2:3] offset:576
	v_add_u32_e32 v175, 0x10000, v175
	v_pk_fma_f32 v[2:3], v[182:183], v[182:183], v[2:3]
	v_pk_fma_f32 v[2:3], v[184:185], v[184:185], v[2:3]
	v_pk_fma_f32 v[2:3], v[186:187], v[186:187], v[2:3]
	v_pk_fma_f32 v[2:3], v[188:189], v[188:189], v[2:3]
	v_pk_mul_f32 v[252:253], v[182:183], v[170:171]
	v_cvt_pk_bf16_f32 v176, v252, v253
	v_pk_mul_f32 v[252:253], v[184:185], v[172:173]
	v_cvt_pk_bf16_f32 v177, v252, v253
	v_pk_mul_f32 v[252:253], v[186:187], v[166:167]
	v_cvt_pk_bf16_f32 v178, v252, v253
	v_pk_mul_f32 v[252:253], v[188:189], v[168:169]
	v_cvt_pk_bf16_f32 v179, v252, v253
	s_nop 1
	v_permlane16_swap_b32_e32 v176, v178
	v_permlane16_swap_b32_e32 v177, v179
	global_store_dwordx4 v165, v[176:179], s[92:93] offset:0
	s_waitcnt vmcnt(11)
	v_pk_fma_f32 v[190:191], v[140:141], v[60:61], v[190:191]
	v_pk_fma_f32 v[192:193], v[142:143], v[62:63], v[192:193]
	v_pk_fma_f32 v[194:195], v[136:137], v[56:57], v[194:195]
	v_pk_fma_f32 v[196:197], v[138:139], v[58:59], v[196:197]
	global_store_dwordx4 v164, v[190:193], s[2:3] offset:512
	global_store_dwordx4 v164, v[194:197], s[2:3] offset:576
	global_load_dwordx4 v[140:143], v175, s[2:3] offset:0
	global_load_dwordx4 v[136:139], v175, s[2:3] offset:64
	v_pk_fma_f32 v[2:3], v[190:191], v[190:191], v[2:3]
	v_pk_fma_f32 v[2:3], v[192:193], v[192:193], v[2:3]
	v_pk_fma_f32 v[2:3], v[194:195], v[194:195], v[2:3]
	v_pk_fma_f32 v[2:3], v[196:197], v[196:197], v[2:3]
	v_pk_mul_f32 v[252:253], v[190:191], v[160:161]
	v_cvt_pk_bf16_f32 v176, v252, v253
	v_pk_mul_f32 v[252:253], v[192:193], v[162:163]
	v_cvt_pk_bf16_f32 v177, v252, v253
	v_pk_mul_f32 v[252:253], v[194:195], v[156:157]
	v_cvt_pk_bf16_f32 v178, v252, v253
	v_pk_mul_f32 v[252:253], v[196:197], v[158:159]
	v_cvt_pk_bf16_f32 v179, v252, v253
	s_nop 1
	v_permlane16_swap_b32_e32 v176, v178
	v_permlane16_swap_b32_e32 v177, v179
	global_store_dwordx4 v165, v[176:179], s[92:93] offset:256
	v_add_f32_e32 v2, v2, v3
	v_mov_b32_e32 v0, v2
	s_nop 1
	v_permlane16_swap_b32_e32 v2, v0
	v_add_f32_e32 v2, v2, v0
	v_mov_b32_e32 v0, v2
	s_nop 1
	v_permlane32_swap_b32_e32 v2, v0
	v_add_f32_e32 v2, v2, v0
	v_lshrrev_b32_e32 v252, 12, v164
	v_lshlrev_b32_e32 v252, 2, v252
	s_mov_b64 exec, 0xffff
	global_atomic_add_f32 v252, v2, s[8:9]
	s_mov_b64 exec, -1
	v_add_u32_e32 v164, 0x10000, v164
	v_add_u32_e32 v165, 0x8000, v165
	v_mov_b32_e32 v2, 0
	v_mov_b32_e32 v3, 0
	s_waitcnt vmcnt(15)
	v_pk_fma_f32 v[198:199], v[132:133], v[72:73], v[198:199]
	v_pk_fma_f32 v[200:201], v[134:135], v[74:75], v[200:201]
	v_pk_fma_f32 v[202:203], v[128:129], v[76:77], v[202:203]
	v_pk_fma_f32 v[204:205], v[130:131], v[78:79], v[204:205]
	global_store_dwordx4 v164, v[198:201], s[2:3] offset:0
	global_store_dwordx4 v164, v[202:205], s[2:3] offset:64
	global_load_dwordx4 v[132:135], v175, s[2:3] offset:512
	global_load_dwordx4 v[128:131], v175, s[2:3] offset:576
	v_add_u32_e32 v175, 0x50000, v175
	v_pk_fma_f32 v[2:3], v[198:199], v[198:199], v[2:3]
	v_pk_fma_f32 v[2:3], v[200:201], v[200:201], v[2:3]
	v_pk_fma_f32 v[2:3], v[202:203], v[202:203], v[2:3]
	v_pk_fma_f32 v[2:3], v[204:205], v[204:205], v[2:3]
	v_pk_mul_f32 v[252:253], v[198:199], v[170:171]
	v_cvt_pk_bf16_f32 v176, v252, v253
	v_pk_mul_f32 v[252:253], v[200:201], v[172:173]
	v_cvt_pk_bf16_f32 v177, v252, v253
	v_pk_mul_f32 v[252:253], v[202:203], v[166:167]
	v_cvt_pk_bf16_f32 v178, v252, v253
	v_pk_mul_f32 v[252:253], v[204:205], v[168:169]
	v_cvt_pk_bf16_f32 v179, v252, v253
	s_nop 1
	v_permlane16_swap_b32_e32 v176, v178
	v_permlane16_swap_b32_e32 v177, v179
	global_store_dwordx4 v165, v[176:179], s[92:93] offset:0
	s_waitcnt vmcnt(18)
; __device__ __forceinline__ unsigned cvt_pk_bf16(float lo, float hi) { unsigned r; asm volatile("v_cvt_pk_bf16_f32 %0, %1, %2" : "=v"(r) : "v"(lo), "v"(hi)); return r; }
;     __device__ __forceinline__ void operator()(const f32x4 (&acc)[2][2][4][2], const Unit& u, int wr, int wc, int fr, int fq) const {
;     ...
;             for (int m = 0; m < 4; ++m) { const size_t row = rowb + ai * HALF + m * 16; const size_t off = row * 1024 + col0; float s = 0.f;
; #pragma unroll
;                 for (int bj = 0; bj < 2; ++bj) { u32x2 w[2];
; #pragma unroll
;                     for (int n = 0; n < 2; ++n) { const f32x4 xv = *(const __attribute__((address_space(1))) f32x4*)(xin + off + bj * HALF + n * 16);
;                         const f32x4 xn = xv + gv[bj][n] * acc[ai][bj][m][n];
;                         *(__attribute__((address_space(1))) f32x4*)(out + off + bj * HALF + n * 16) = xn;
;                         if (XG) { s += (xn[0] * xn[0] + xn[1] * xn[1]) + (xn[2] * xn[2] + xn[3] * xn[3]); const f32x4 t = xn * Gv[bj][n];
;                             w[n].x = cvt_pk_bf16(t[0], t[1]); w[n].y = cvt_pk_bf16(t[2], t[3]); } }
;                     if (XG) {
;                         const bool odd = (fq & 1) != 0; const u32x2 snd = odd ? w[0] : w[1]; u32x2 rcv; rcv.x = __shfl_xor(snd.x, 16); rcv.y = __shfl_xor(snd.y, 16);
;                         u32x4 o4; if (odd) { o4.x = rcv.x; o4.y = rcv.y; o4.z = w[1].x; o4.w = w[1].y; } else { o4.x = w[0].x; o4.y = w[0].y; o4.z = rcv.x; o4.w = rcv.y; }
;                         *(u32x4*)(XG + off + bj * HALF + (odd ? 12 : 0)) = o4; } }
;                 if (XG) { s += __shfl_xor(s, 16); s += __shfl_xor(s, 32); if (fq == 0) atomicAdd(ssq + row, s); } }
	v_pk_fma_f32 v[236:237], v[124:125], v[60:61], v[236:237]
	v_pk_fma_f32 v[238:239], v[126:127], v[62:63], v[238:239]
	v_pk_fma_f32 v[240:241], v[120:121], v[56:57], v[240:241]
	v_pk_fma_f32 v[242:243], v[122:123], v[58:59], v[242:243]
	global_store_dwordx4 v164, v[236:239], s[2:3] offset:512
	global_store_dwordx4 v164, v[240:243], s[2:3] offset:576
	global_load_dwordx4 v[124:127], v175, s[2:3] offset:0
	global_load_dwordx4 v[120:123], v175, s[2:3] offset:64
	v_pk_fma_f32 v[2:3], v[236:237], v[236:237], v[2:3]
	v_pk_fma_f32 v[2:3], v[238:239], v[238:239], v[2:3]
	v_pk_fma_f32 v[2:3], v[240:241], v[240:241], v[2:3]
	v_pk_fma_f32 v[2:3], v[242:243], v[242:243], v[2:3]
	v_pk_mul_f32 v[252:253], v[236:237], v[160:161]
	v_cvt_pk_bf16_f32 v176, v252, v253
	v_pk_mul_f32 v[252:253], v[238:239], v[162:163]
	v_cvt_pk_bf16_f32 v177, v252, v253
	v_pk_mul_f32 v[252:253], v[240:241], v[156:157]
	v_cvt_pk_bf16_f32 v178, v252, v253
	v_pk_mul_f32 v[252:253], v[242:243], v[158:159]
	v_cvt_pk_bf16_f32 v179, v252, v253
	s_nop 1
	v_permlane16_swap_b32_e32 v176, v178
	v_permlane16_swap_b32_e32 v177, v179
	global_store_dwordx4 v165, v[176:179], s[92:93] offset:256
	v_add_f32_e32 v2, v2, v3
	v_mov_b32_e32 v0, v2
	s_nop 1
	v_permlane16_swap_b32_e32 v2, v0
	v_add_f32_e32 v2, v2, v0
	v_mov_b32_e32 v0, v2
	s_nop 1
	v_permlane32_swap_b32_e32 v2, v0
	v_add_f32_e32 v2, v2, v0
	v_lshrrev_b32_e32 v252, 12, v164
	v_lshlrev_b32_e32 v252, 2, v252
	s_mov_b64 exec, 0xffff
	global_atomic_add_f32 v252, v2, s[8:9]
	s_mov_b64 exec, -1
	v_add_u32_e32 v164, 0x10000, v164
	v_add_u32_e32 v165, 0x8000, v165
	v_mov_b32_e32 v2, 0
	v_mov_b32_e32 v3, 0
	s_waitcnt vmcnt(22)
	v_pk_fma_f32 v[244:245], v[116:117], v[72:73], v[244:245]
	v_pk_fma_f32 v[246:247], v[118:119], v[74:75], v[246:247]
	v_pk_fma_f32 v[248:249], v[112:113], v[76:77], v[248:249]
	v_pk_fma_f32 v[250:251], v[114:115], v[78:79], v[250:251]
	global_store_dwordx4 v164, v[244:247], s[2:3] offset:0
	global_store_dwordx4 v164, v[248:251], s[2:3] offset:64
	global_load_dwordx4 v[116:119], v175, s[2:3] offset:512
	global_load_dwordx4 v[112:115], v175, s[2:3] offset:576
	v_add_u32_e32 v175, 0x10000, v175
	v_pk_fma_f32 v[2:3], v[244:245], v[244:245], v[2:3]
	v_pk_fma_f32 v[2:3], v[246:247], v[246:247], v[2:3]
	v_pk_fma_f32 v[2:3], v[248:249], v[248:249], v[2:3]
	v_pk_fma_f32 v[2:3], v[250:251], v[250:251], v[2:3]
	v_pk_mul_f32 v[252:253], v[244:245], v[170:171]
	v_cvt_pk_bf16_f32 v176, v252, v253
	v_pk_mul_f32 v[252:253], v[246:247], v[172:173]
	v_cvt_pk_bf16_f32 v177, v252, v253
	v_pk_mul_f32 v[252:253], v[248:249], v[166:167]
	v_cvt_pk_bf16_f32 v178, v252, v253
	v_pk_mul_f32 v[252:253], v[250:251], v[168:169]
	v_cvt_pk_bf16_f32 v179, v252, v253
	s_nop 1
	v_permlane16_swap_b32_e32 v176, v178
	v_permlane16_swap_b32_e32 v177, v179
	global_store_dwordx4 v165, v[176:179], s[92:93] offset:0
	s_waitcnt vmcnt(23)
	v_pk_fma_f32 v[64:65], v[108:109], v[60:61], v[64:65]
	v_pk_fma_f32 v[66:67], v[110:111], v[62:63], v[66:67]
	v_pk_fma_f32 v[144:145], v[104:105], v[56:57], v[144:145]
	v_pk_fma_f32 v[146:147], v[106:107], v[58:59], v[146:147]
	global_store_dwordx4 v164, v[64:67], s[2:3] offset:512
	global_store_dwordx4 v164, v[144:147], s[2:3] offset:576
	global_load_dwordx4 v[108:111], v175, s[2:3] offset:0
	global_load_dwordx4 v[104:107], v175, s[2:3] offset:64
	v_pk_fma_f32 v[2:3], v[64:65], v[64:65], v[2:3]
	v_pk_fma_f32 v[2:3], v[66:67], v[66:67], v[2:3]
	v_pk_fma_f32 v[2:3], v[144:145], v[144:145], v[2:3]
	v_pk_fma_f32 v[2:3], v[146:147], v[146:147], v[2:3]
	v_pk_mul_f32 v[252:253], v[64:65], v[160:161]
	v_cvt_pk_bf16_f32 v176, v252, v253
	v_pk_mul_f32 v[252:253], v[66:67], v[162:163]
	v_cvt_pk_bf16_f32 v177, v252, v253
	v_pk_mul_f32 v[252:253], v[144:145], v[156:157]
	v_cvt_pk_bf16_f32 v178, v252, v253
	v_pk_mul_f32 v[252:253], v[146:147], v[158:159]
	v_cvt_pk_bf16_f32 v179, v252, v253
	s_nop 1
	v_permlane16_swap_b32_e32 v176, v178
	v_permlane16_swap_b32_e32 v177, v179
	global_store_dwordx4 v165, v[176:179], s[92:93] offset:256
	v_add_f32_e32 v2, v2, v3
	v_mov_b32_e32 v0, v2
	s_nop 1
	v_permlane16_swap_b32_e32 v2, v0
	v_add_f32_e32 v2, v2, v0
	v_mov_b32_e32 v0, v2
	s_nop 1
	v_permlane32_swap_b32_e32 v2, v0
	v_add_f32_e32 v2, v2, v0
	v_lshrrev_b32_e32 v252, 12, v164
	v_lshlrev_b32_e32 v252, 2, v252
	s_mov_b64 exec, 0xffff
	global_atomic_add_f32 v252, v2, s[8:9]
	s_mov_b64 exec, -1
	v_add_u32_e32 v164, 0x10000, v164
	v_add_u32_e32 v165, 0x8000, v165
	v_mov_b32_e32 v2, 0
	v_mov_b32_e32 v3, 0
	s_waitcnt vmcnt(24)
	v_pk_fma_f32 v[140:141], v[100:101], v[72:73], v[140:141]
	v_pk_fma_f32 v[142:143], v[102:103], v[74:75], v[142:143]
	v_pk_fma_f32 v[136:137], v[96:97], v[76:77], v[136:137]
	v_pk_fma_f32 v[138:139], v[98:99], v[78:79], v[138:139]
	global_store_dwordx4 v164, v[140:143], s[2:3] offset:0
	global_store_dwordx4 v164, v[136:139], s[2:3] offset:64
	global_load_dwordx4 v[100:103], v175, s[2:3] offset:512
	global_load_dwordx4 v[96:99], v175, s[2:3] offset:576
	v_add_u32_e32 v175, 0x10000, v175
	v_pk_fma_f32 v[2:3], v[140:141], v[140:141], v[2:3]
	v_pk_fma_f32 v[2:3], v[142:143], v[142:143], v[2:3]
	v_pk_fma_f32 v[2:3], v[136:137], v[136:137], v[2:3]
	v_pk_fma_f32 v[2:3], v[138:139], v[138:139], v[2:3]
	v_pk_mul_f32 v[252:253], v[140:141], v[170:171]
	v_cvt_pk_bf16_f32 v176, v252, v253
	v_pk_mul_f32 v[252:253], v[142:143], v[172:173]
	v_cvt_pk_bf16_f32 v177, v252, v253
	v_pk_mul_f32 v[252:253], v[136:137], v[166:167]
	v_cvt_pk_bf16_f32 v178, v252, v253
	v_pk_mul_f32 v[252:253], v[138:139], v[168:169]
	v_cvt_pk_bf16_f32 v179, v252, v253
	s_nop 1
	v_permlane16_swap_b32_e32 v176, v178
	v_permlane16_swap_b32_e32 v177, v179
	global_store_dwordx4 v165, v[176:179], s[92:93] offset:0
	s_waitcnt vmcnt(23)
; __device__ __forceinline__ unsigned cvt_pk_bf16(float lo, float hi) { unsigned r; asm volatile("v_cvt_pk_bf16_f32 %0, %1, %2" : "=v"(r) : "v"(lo), "v"(hi)); return r; }
;     __device__ __forceinline__ void operator()(const f32x4 (&acc)[2][2][4][2], const Unit& u, int wr, int wc, int fr, int fq) const {
;     ...
;             for (int m = 0; m < 4; ++m) { const size_t row = rowb + ai * HALF + m * 16; const size_t off = row * 1024 + col0; float s = 0.f;
; #pragma unroll
;                 for (int bj = 0; bj < 2; ++bj) { u32x2 w[2];
; #pragma unroll
;                     for (int n = 0; n < 2; ++n) { const f32x4 xv = *(const __attribute__((address_space(1))) f32x4*)(xin + off + bj * HALF + n * 16);
;                         const f32x4 xn = xv + gv[bj][n] * acc[ai][bj][m][n];
;                         *(__attribute__((address_space(1))) f32x4*)(out + off + bj * HALF + n * 16) = xn;
;                         if (XG) { s += (xn[0] * xn[0] + xn[1] * xn[1]) + (xn[2] * xn[2] + xn[3] * xn[3]); const f32x4 t = xn * Gv[bj][n];
;                             w[n].x = cvt_pk_bf16(t[0], t[1]); w[n].y = cvt_pk_bf16(t[2], t[3]); } }
;                     if (XG) {
;                         const bool odd = (fq & 1) != 0; const u32x2 snd = odd ? w[0] : w[1]; u32x2 rcv; rcv.x = __shfl_xor(snd.x, 16); rcv.y = __shfl_xor(snd.y, 16);
;                         u32x4 o4; if (odd) { o4.x = rcv.x; o4.y = rcv.y; o4.z = w[1].x; o4.w = w[1].y; } else { o4.x = w[0].x; o4.y = w[0].y; o4.z = rcv.x; o4.w = rcv.y; }
;                         *(u32x4*)(XG + off + bj * HALF + (odd ? 12 : 0)) = o4; } }
;                 if (XG) { s += __shfl_xor(s, 16); s += __shfl_xor(s, 32); if (fq == 0) atomicAdd(ssq + row, s); } }
	v_pk_fma_f32 v[132:133], v[92:93], v[60:61], v[132:133]
	v_pk_fma_f32 v[134:135], v[94:95], v[62:63], v[134:135]
	v_pk_fma_f32 v[128:129], v[88:89], v[56:57], v[128:129]
	v_pk_fma_f32 v[130:131], v[90:91], v[58:59], v[130:131]
	global_store_dwordx4 v164, v[132:135], s[2:3] offset:512
	global_store_dwordx4 v164, v[128:131], s[2:3] offset:576
	global_load_dwordx4 v[92:95], v175, s[2:3] offset:0
	global_load_dwordx4 v[88:91], v175, s[2:3] offset:64
	v_pk_fma_f32 v[2:3], v[132:133], v[132:133], v[2:3]
	v_pk_fma_f32 v[2:3], v[134:135], v[134:135], v[2:3]
	v_pk_fma_f32 v[2:3], v[128:129], v[128:129], v[2:3]
	v_pk_fma_f32 v[2:3], v[130:131], v[130:131], v[2:3]
	v_pk_mul_f32 v[252:253], v[132:133], v[160:161]
	v_cvt_pk_bf16_f32 v176, v252, v253
	v_pk_mul_f32 v[252:253], v[134:135], v[162:163]
	v_cvt_pk_bf16_f32 v177, v252, v253
	v_pk_mul_f32 v[252:253], v[128:129], v[156:157]
	v_cvt_pk_bf16_f32 v178, v252, v253
	v_pk_mul_f32 v[252:253], v[130:131], v[158:159]
	v_cvt_pk_bf16_f32 v179, v252, v253
	s_nop 1
	v_permlane16_swap_b32_e32 v176, v178
	v_permlane16_swap_b32_e32 v177, v179
	global_store_dwordx4 v165, v[176:179], s[92:93] offset:256
	v_add_f32_e32 v2, v2, v3
	v_mov_b32_e32 v0, v2
	s_nop 1
	v_permlane16_swap_b32_e32 v2, v0
	v_add_f32_e32 v2, v2, v0
	v_mov_b32_e32 v0, v2
	s_nop 1
	v_permlane32_swap_b32_e32 v2, v0
	v_add_f32_e32 v2, v2, v0
	v_lshrrev_b32_e32 v252, 12, v164
	v_lshlrev_b32_e32 v252, 2, v252
	s_mov_b64 exec, 0xffff
	global_atomic_add_f32 v252, v2, s[8:9]
	s_mov_b64 exec, -1
	v_add_u32_e32 v164, 0x50000, v164
	v_add_u32_e32 v165, 0x28000, v165
	v_mov_b32_e32 v2, 0
	v_mov_b32_e32 v3, 0
	s_waitcnt vmcnt(24)
	v_pk_fma_f32 v[124:125], v[84:85], v[72:73], v[124:125]
	v_pk_fma_f32 v[126:127], v[86:87], v[74:75], v[126:127]
	v_pk_fma_f32 v[120:121], v[80:81], v[76:77], v[120:121]
	v_pk_fma_f32 v[122:123], v[82:83], v[78:79], v[122:123]
	global_store_dwordx4 v164, v[124:127], s[2:3] offset:0
	global_store_dwordx4 v164, v[120:123], s[2:3] offset:64
	global_load_dwordx4 v[84:87], v175, s[2:3] offset:512
	global_load_dwordx4 v[80:83], v175, s[2:3] offset:576
	v_add_u32_e32 v175, 0x10000, v175
	v_pk_fma_f32 v[2:3], v[124:125], v[124:125], v[2:3]
	v_pk_fma_f32 v[2:3], v[126:127], v[126:127], v[2:3]
	v_pk_fma_f32 v[2:3], v[120:121], v[120:121], v[2:3]
	v_pk_fma_f32 v[2:3], v[122:123], v[122:123], v[2:3]
	v_pk_mul_f32 v[252:253], v[124:125], v[170:171]
	v_cvt_pk_bf16_f32 v176, v252, v253
	v_pk_mul_f32 v[252:253], v[126:127], v[172:173]
	v_cvt_pk_bf16_f32 v177, v252, v253
	v_pk_mul_f32 v[252:253], v[120:121], v[166:167]
	v_cvt_pk_bf16_f32 v178, v252, v253
	v_pk_mul_f32 v[252:253], v[122:123], v[168:169]
	v_cvt_pk_bf16_f32 v179, v252, v253
	s_nop 1
	v_permlane16_swap_b32_e32 v176, v178
	v_permlane16_swap_b32_e32 v177, v179
	global_store_dwordx4 v165, v[176:179], s[92:93] offset:0
	s_waitcnt vmcnt(23)
	v_pk_fma_f32 v[116:117], v[68:69], v[60:61], v[116:117]
	v_pk_fma_f32 v[118:119], v[70:71], v[62:63], v[118:119]
	v_pk_fma_f32 v[112:113], v[52:53], v[56:57], v[112:113]
	v_pk_fma_f32 v[114:115], v[54:55], v[58:59], v[114:115]
	global_store_dwordx4 v164, v[116:119], s[2:3] offset:512
	global_store_dwordx4 v164, v[112:115], s[2:3] offset:576
	global_load_dwordx4 v[68:71], v175, s[2:3] offset:0
	global_load_dwordx4 v[52:55], v175, s[2:3] offset:64
	v_pk_fma_f32 v[2:3], v[116:117], v[116:117], v[2:3]
	v_pk_fma_f32 v[2:3], v[118:119], v[118:119], v[2:3]
	v_pk_fma_f32 v[2:3], v[112:113], v[112:113], v[2:3]
	v_pk_fma_f32 v[2:3], v[114:115], v[114:115], v[2:3]
	v_pk_mul_f32 v[252:253], v[116:117], v[160:161]
	v_cvt_pk_bf16_f32 v176, v252, v253
	v_pk_mul_f32 v[252:253], v[118:119], v[162:163]
	v_cvt_pk_bf16_f32 v177, v252, v253
	v_pk_mul_f32 v[252:253], v[112:113], v[156:157]
	v_cvt_pk_bf16_f32 v178, v252, v253
	v_pk_mul_f32 v[252:253], v[114:115], v[158:159]
	v_cvt_pk_bf16_f32 v179, v252, v253
	s_nop 1
	v_permlane16_swap_b32_e32 v176, v178
	v_permlane16_swap_b32_e32 v177, v179
	global_store_dwordx4 v165, v[176:179], s[92:93] offset:256
	v_add_f32_e32 v2, v2, v3
	v_mov_b32_e32 v0, v2
	s_nop 1
	v_permlane16_swap_b32_e32 v2, v0
	v_add_f32_e32 v2, v2, v0
	v_mov_b32_e32 v0, v2
	s_nop 1
	v_permlane32_swap_b32_e32 v2, v0
	v_add_f32_e32 v2, v2, v0
	v_lshrrev_b32_e32 v252, 12, v164
	v_lshlrev_b32_e32 v252, 2, v252
	s_mov_b64 exec, 0xffff
	global_atomic_add_f32 v252, v2, s[8:9]
	s_mov_b64 exec, -1
	v_add_u32_e32 v164, 0x10000, v164
	v_add_u32_e32 v165, 0x8000, v165
	v_mov_b32_e32 v2, 0
	v_mov_b32_e32 v3, 0
	s_waitcnt vmcnt(24)
	v_pk_fma_f32 v[108:109], v[48:49], v[72:73], v[108:109]
	v_pk_fma_f32 v[110:111], v[50:51], v[74:75], v[110:111]
	v_pk_fma_f32 v[104:105], v[44:45], v[76:77], v[104:105]
	v_pk_fma_f32 v[106:107], v[46:47], v[78:79], v[106:107]
	global_store_dwordx4 v164, v[108:111], s[2:3] offset:0
	global_store_dwordx4 v164, v[104:107], s[2:3] offset:64
	global_load_dwordx4 v[48:51], v175, s[2:3] offset:512
	global_load_dwordx4 v[44:47], v175, s[2:3] offset:576
	v_pk_fma_f32 v[2:3], v[108:109], v[108:109], v[2:3]
	v_pk_fma_f32 v[2:3], v[110:111], v[110:111], v[2:3]
	v_pk_fma_f32 v[2:3], v[104:105], v[104:105], v[2:3]
	v_pk_fma_f32 v[2:3], v[106:107], v[106:107], v[2:3]
	v_pk_mul_f32 v[252:253], v[108:109], v[170:171]
	v_cvt_pk_bf16_f32 v176, v252, v253
	v_pk_mul_f32 v[252:253], v[110:111], v[172:173]
	v_cvt_pk_bf16_f32 v177, v252, v253
	v_pk_mul_f32 v[252:253], v[104:105], v[166:167]
	v_cvt_pk_bf16_f32 v178, v252, v253
	v_pk_mul_f32 v[252:253], v[106:107], v[168:169]
	v_cvt_pk_bf16_f32 v179, v252, v253
	s_nop 1
	v_permlane16_swap_b32_e32 v176, v178
	v_permlane16_swap_b32_e32 v177, v179
	global_store_dwordx4 v165, v[176:179], s[92:93] offset:0
	s_waitcnt vmcnt(23)
; __device__ __forceinline__ unsigned cvt_pk_bf16(float lo, float hi) { unsigned r; asm volatile("v_cvt_pk_bf16_f32 %0, %1, %2" : "=v"(r) : "v"(lo), "v"(hi)); return r; }
;     __device__ __forceinline__ void operator()(const f32x4 (&acc)[2][2][4][2], const Unit& u, int wr, int wc, int fr, int fq) const {
;     ...
;             for (int m = 0; m < 4; ++m) { const size_t row = rowb + ai * HALF + m * 16; const size_t off = row * 1024 + col0; float s = 0.f;
; #pragma unroll
;                 for (int bj = 0; bj < 2; ++bj) { u32x2 w[2];
; #pragma unroll
;                     for (int n = 0; n < 2; ++n) { const f32x4 xv = *(const __attribute__((address_space(1))) f32x4*)(xin + off + bj * HALF + n * 16);
;                         const f32x4 xn = xv + gv[bj][n] * acc[ai][bj][m][n];
;                         *(__attribute__((address_space(1))) f32x4*)(out + off + bj * HALF + n * 16) = xn;
;                         if (XG) { s += (xn[0] * xn[0] + xn[1] * xn[1]) + (xn[2] * xn[2] + xn[3] * xn[3]); const f32x4 t = xn * Gv[bj][n];
;                             w[n].x = cvt_pk_bf16(t[0], t[1]); w[n].y = cvt_pk_bf16(t[2], t[3]); } }
;                     if (XG) {
;                         const bool odd = (fq & 1) != 0; const u32x2 snd = odd ? w[0] : w[1]; u32x2 rcv; rcv.x = __shfl_xor(snd.x, 16); rcv.y = __shfl_xor(snd.y, 16);
;                         u32x4 o4; if (odd) { o4.x = rcv.x; o4.y = rcv.y; o4.z = w[1].x; o4.w = w[1].y; } else { o4.x = w[0].x; o4.y = w[0].y; o4.z = rcv.x; o4.w = rcv.y; }
;                         *(u32x4*)(XG + off + bj * HALF + (odd ? 12 : 0)) = o4; } }
;                 if (XG) { s += __shfl_xor(s, 16); s += __shfl_xor(s, 32); if (fq == 0) atomicAdd(ssq + row, s); } }
	v_pk_fma_f32 v[100:101], v[40:41], v[60:61], v[100:101]
	v_pk_fma_f32 v[102:103], v[42:43], v[62:63], v[102:103]
	v_pk_fma_f32 v[96:97], v[36:37], v[56:57], v[96:97]
	v_pk_fma_f32 v[98:99], v[38:39], v[58:59], v[98:99]
	global_store_dwordx4 v164, v[100:103], s[2:3] offset:512
	global_store_dwordx4 v164, v[96:99], s[2:3] offset:576
	v_pk_fma_f32 v[2:3], v[100:101], v[100:101], v[2:3]
	v_pk_fma_f32 v[2:3], v[102:103], v[102:103], v[2:3]
	v_pk_fma_f32 v[2:3], v[96:97], v[96:97], v[2:3]
	v_pk_fma_f32 v[2:3], v[98:99], v[98:99], v[2:3]
	v_pk_mul_f32 v[252:253], v[100:101], v[160:161]
	v_cvt_pk_bf16_f32 v176, v252, v253
	v_pk_mul_f32 v[252:253], v[102:103], v[162:163]
	v_cvt_pk_bf16_f32 v177, v252, v253
	v_pk_mul_f32 v[252:253], v[96:97], v[156:157]
	v_cvt_pk_bf16_f32 v178, v252, v253
	v_pk_mul_f32 v[252:253], v[98:99], v[158:159]
	v_cvt_pk_bf16_f32 v179, v252, v253
	s_nop 1
	v_permlane16_swap_b32_e32 v176, v178
	v_permlane16_swap_b32_e32 v177, v179
	global_store_dwordx4 v165, v[176:179], s[92:93] offset:256
	v_add_f32_e32 v2, v2, v3
	v_mov_b32_e32 v0, v2
	s_nop 1
	v_permlane16_swap_b32_e32 v2, v0
	v_add_f32_e32 v2, v2, v0
	v_mov_b32_e32 v0, v2
	s_nop 1
	v_permlane32_swap_b32_e32 v2, v0
	v_add_f32_e32 v2, v2, v0
	v_lshrrev_b32_e32 v252, 12, v164
	v_lshlrev_b32_e32 v252, 2, v252
	s_mov_b64 exec, 0xffff
	global_atomic_add_f32 v252, v2, s[8:9]
	s_mov_b64 exec, -1
	v_add_u32_e32 v164, 0x10000, v164
	v_add_u32_e32 v165, 0x8000, v165
	v_mov_b32_e32 v2, 0
	v_mov_b32_e32 v3, 0
	s_waitcnt vmcnt(22)
	v_pk_fma_f32 v[92:93], v[32:33], v[72:73], v[92:93]
	v_pk_fma_f32 v[94:95], v[34:35], v[74:75], v[94:95]
	v_pk_fma_f32 v[88:89], v[28:29], v[76:77], v[88:89]
	v_pk_fma_f32 v[90:91], v[30:31], v[78:79], v[90:91]
	global_store_dwordx4 v164, v[92:95], s[2:3] offset:0
	global_store_dwordx4 v164, v[88:91], s[2:3] offset:64
	v_pk_fma_f32 v[2:3], v[92:93], v[92:93], v[2:3]
	v_pk_fma_f32 v[2:3], v[94:95], v[94:95], v[2:3]
	v_pk_fma_f32 v[2:3], v[88:89], v[88:89], v[2:3]
	v_pk_fma_f32 v[2:3], v[90:91], v[90:91], v[2:3]
	v_pk_mul_f32 v[252:253], v[92:93], v[170:171]
	v_cvt_pk_bf16_f32 v176, v252, v253
	v_pk_mul_f32 v[252:253], v[94:95], v[172:173]
	v_cvt_pk_bf16_f32 v177, v252, v253
	v_pk_mul_f32 v[252:253], v[88:89], v[166:167]
	v_cvt_pk_bf16_f32 v178, v252, v253
	v_pk_mul_f32 v[252:253], v[90:91], v[168:169]
	v_cvt_pk_bf16_f32 v179, v252, v253
	s_nop 1
	v_permlane16_swap_b32_e32 v176, v178
	v_permlane16_swap_b32_e32 v177, v179
	global_store_dwordx4 v165, v[176:179], s[92:93] offset:0
	s_waitcnt vmcnt(19)
	v_pk_fma_f32 v[84:85], v[24:25], v[60:61], v[84:85]
	v_pk_fma_f32 v[86:87], v[26:27], v[62:63], v[86:87]
	v_pk_fma_f32 v[80:81], v[20:21], v[56:57], v[80:81]
	v_pk_fma_f32 v[82:83], v[22:23], v[58:59], v[82:83]
	global_store_dwordx4 v164, v[84:87], s[2:3] offset:512
	global_store_dwordx4 v164, v[80:83], s[2:3] offset:576
	v_pk_fma_f32 v[2:3], v[84:85], v[84:85], v[2:3]
	v_pk_fma_f32 v[2:3], v[86:87], v[86:87], v[2:3]
	v_pk_fma_f32 v[2:3], v[80:81], v[80:81], v[2:3]
	v_pk_fma_f32 v[2:3], v[82:83], v[82:83], v[2:3]
	v_pk_mul_f32 v[252:253], v[84:85], v[160:161]
	v_cvt_pk_bf16_f32 v176, v252, v253
	v_pk_mul_f32 v[252:253], v[86:87], v[162:163]
	v_cvt_pk_bf16_f32 v177, v252, v253
	v_pk_mul_f32 v[252:253], v[80:81], v[156:157]
	v_cvt_pk_bf16_f32 v178, v252, v253
	v_pk_mul_f32 v[252:253], v[82:83], v[158:159]
	v_cvt_pk_bf16_f32 v179, v252, v253
	s_nop 1
	v_permlane16_swap_b32_e32 v176, v178
	v_permlane16_swap_b32_e32 v177, v179
	global_store_dwordx4 v165, v[176:179], s[92:93] offset:256
	v_add_f32_e32 v2, v2, v3
	v_mov_b32_e32 v0, v2
	s_nop 1
	v_permlane16_swap_b32_e32 v2, v0
	v_add_f32_e32 v2, v2, v0
	v_mov_b32_e32 v0, v2
	s_nop 1
	v_permlane32_swap_b32_e32 v2, v0
	v_add_f32_e32 v2, v2, v0
	v_lshrrev_b32_e32 v252, 12, v164
	v_lshlrev_b32_e32 v252, 2, v252
	s_mov_b64 exec, 0xffff
	global_atomic_add_f32 v252, v2, s[8:9]
	s_mov_b64 exec, -1
	v_add_u32_e32 v164, 0x10000, v164
	v_add_u32_e32 v165, 0x8000, v165
	v_mov_b32_e32 v2, 0
	v_mov_b32_e32 v3, 0
	s_waitcnt vmcnt(18)
	v_pk_fma_f32 v[68:69], v[16:17], v[72:73], v[68:69]
	v_pk_fma_f32 v[70:71], v[18:19], v[74:75], v[70:71]
	v_pk_fma_f32 v[52:53], v[12:13], v[76:77], v[52:53]
	v_pk_fma_f32 v[54:55], v[14:15], v[78:79], v[54:55]
	global_store_dwordx4 v164, v[68:71], s[2:3] offset:0
	global_store_dwordx4 v164, v[52:55], s[2:3] offset:64
	v_pk_fma_f32 v[2:3], v[68:69], v[68:69], v[2:3]
	v_pk_fma_f32 v[2:3], v[70:71], v[70:71], v[2:3]
	v_pk_fma_f32 v[2:3], v[52:53], v[52:53], v[2:3]
	v_pk_fma_f32 v[2:3], v[54:55], v[54:55], v[2:3]
	v_pk_mul_f32 v[252:253], v[68:69], v[170:171]
	v_cvt_pk_bf16_f32 v176, v252, v253
	v_pk_mul_f32 v[252:253], v[70:71], v[172:173]
	v_cvt_pk_bf16_f32 v177, v252, v253
	v_pk_mul_f32 v[252:253], v[52:53], v[166:167]
	v_cvt_pk_bf16_f32 v178, v252, v253
	v_pk_mul_f32 v[252:253], v[54:55], v[168:169]
	v_cvt_pk_bf16_f32 v179, v252, v253
	s_nop 1
	v_permlane16_swap_b32_e32 v176, v178
	v_permlane16_swap_b32_e32 v177, v179
	global_store_dwordx4 v165, v[176:179], s[92:93] offset:0
	s_waitcnt vmcnt(15)
	v_pk_fma_f32 v[48:49], v[8:9], v[60:61], v[48:49]
	v_pk_fma_f32 v[50:51], v[10:11], v[62:63], v[50:51]
	v_pk_fma_f32 v[44:45], v[4:5], v[56:57], v[44:45]
	v_pk_fma_f32 v[46:47], v[6:7], v[58:59], v[46:47]
	global_store_dwordx4 v164, v[48:51], s[2:3] offset:512
	global_store_dwordx4 v164, v[44:47], s[2:3] offset:576
	v_pk_fma_f32 v[2:3], v[48:49], v[48:49], v[2:3]
	v_pk_fma_f32 v[2:3], v[50:51], v[50:51], v[2:3]
	v_pk_fma_f32 v[2:3], v[44:45], v[44:45], v[2:3]
	v_pk_fma_f32 v[2:3], v[46:47], v[46:47], v[2:3]
	v_pk_mul_f32 v[252:253], v[48:49], v[160:161]
	v_cvt_pk_bf16_f32 v176, v252, v253
	v_pk_mul_f32 v[252:253], v[50:51], v[162:163]
	v_cvt_pk_bf16_f32 v177, v252, v253
	v_pk_mul_f32 v[252:253], v[44:45], v[156:157]
	v_cvt_pk_bf16_f32 v178, v252, v253
	v_pk_mul_f32 v[252:253], v[46:47], v[158:159]
	v_cvt_pk_bf16_f32 v179, v252, v253
	s_nop 1
	v_permlane16_swap_b32_e32 v176, v178
	v_permlane16_swap_b32_e32 v177, v179
	global_store_dwordx4 v165, v[176:179], s[92:93] offset:256
	v_add_f32_e32 v2, v2, v3
	v_mov_b32_e32 v0, v2
	s_nop 1
	v_permlane16_swap_b32_e32 v2, v0
	v_add_f32_e32 v2, v2, v0
	v_mov_b32_e32 v0, v2
	s_nop 1
	v_permlane32_swap_b32_e32 v2, v0
	v_add_f32_e32 v2, v2, v0
	v_lshrrev_b32_e32 v252, 12, v164
	v_lshlrev_b32_e32 v252, 2, v252
	s_mov_b64 exec, 0xffff
	global_atomic_add_f32 v252, v2, s[8:9]
	s_mov_b64 exec, -1
	s_branch .LBB0_823
; __device__ __forceinline__ unsigned cvt_pk_bf16(float lo, float hi) { unsigned r; asm volatile("v_cvt_pk_bf16_f32 %0, %1, %2" : "=v"(r) : "v"(lo), "v"(hi)); return r; }
;     __device__ __forceinline__ void operator()(const f32x4 (&acc)[2][2][4][2], const Unit& u, int wr, int wc, int fr, int fq) const {
;     ...
;                     for (int n = 0; n < 2; ++n) { const f32x4 xv = *(const __attribute__((address_space(1))) f32x4*)(xin + off + bj * HALF + n * 16);
;                         const f32x4 xn = xv + gv[bj][n] * acc[ai][bj][m][n];
;                         *(__attribute__((address_space(1))) f32x4*)(out + off + bj * HALF + n * 16) = xn;
;                         if (XG) { s += (xn[0] * xn[0] + xn[1] * xn[1]) + (xn[2] * xn[2] + xn[3] * xn[3]); const f32x4 t = xn * Gv[bj][n];
;                             w[n].x = cvt_pk_bf16(t[0], t[1]); w[n].y = cvt_pk_bf16(t[2], t[3]); } }
.Lepi_ffn2_orig:
	v_lshlrev_b64 v[2:3], 10, v[174:175]
	v_lshl_add_u64 v[176:177], v[2:3], 0, v[164:165]
	v_lshl_add_u64 v[178:179], v[176:177], 2, s[2:3]
	global_load_dwordx4 v[184:187], v[178:179], off
	s_and_b64 vcc, exec, s[42:43]
	s_waitcnt vmcnt(0)
	v_pk_fma_f32 v[66:67], v[66:67], v[74:75], v[186:187]
	v_pk_fma_f32 v[64:65], v[64:65], v[72:73], v[184:185]
	global_store_dwordx4 v[178:179], v[64:67], off
	s_cbranch_vccnz .LBB0_704
	v_pk_mul_f32 v[2:3], v[66:67], v[66:67]
	v_pk_mul_f32 v[184:185], v[64:65], v[64:65]
	v_pk_mul_f32 v[64:65], v[170:171], v[64:65]
	v_pk_mov_b32 v[186:187], v[184:185], v[2:3] op_sel:[1,0]
	v_mov_b32_e32 v185, v3
	v_pk_add_f32 v[2:3], v[186:187], v[184:185]
	v_cvt_pk_bf16_f32 v64, v64, v65
	s_nop 0
	v_add_f32_e32 v184, v2, v3
	v_pk_mul_f32 v[2:3], v[172:173], v[66:67]
	v_mov_b32_e32 v66, v1
	v_mov_b32_e32 v67, v1
	v_cvt_pk_bf16_f32 v65, v2, v3
	s_branch .LBB0_705
